# QKV and ukv epilogue heads: per-row sum-of-squares loads hoisted (8 serialized load round trips -> 2 / 1 per tile, counted vmcnt), on top of v18
# baseline (speedup 1.0000x reference)
.LBB0_302:
	s_ashr_i32 s65, s64, 31
	v_mov_b32_e32 v142, v1
	v_mov_b32_e32 v183, v180
	s_lshl_b64 s[0:1], s[64:65], 12
	v_readlane_b32 s5, v251, 59
	s_add_u32 s0, s5, s0
	v_add_u32_e32 v160, s68, v142
	v_readlane_b32 s5, v251, 60
	v_ashrrev_i32_e32 v161, 31, v160
	s_addc_u32 s1, s5, s1
	v_lshl_add_u64 v[144:145], v[160:161], 4, s[0:1]
	global_load_dwordx4 v[184:187], v[144:145], off
	global_load_dwordx4 v[188:191], v[144:145], off offset:256
	global_load_dwordx4 v[192:195], v[144:145], off offset:512
	global_load_dwordx4 v[196:199], v[144:145], off offset:768
	global_load_dwordx4 v[200:203], v[144:145], off offset:2048
	global_load_dwordx4 v[204:207], v[144:145], off offset:2304
	global_load_dwordx4 v[208:211], v[144:145], off offset:2560
	global_load_dwordx4 v[212:215], v[144:145], off offset:2816
	s_waitcnt vmcnt(7)
	v_mov_b64_e32 v[144:145], v[184:185]
	v_mov_b64_e32 v[146:147], v[186:187]
	v_mov_b32_e32 v148, v145
	v_mov_b32_e32 v149, v146
	v_mov_b32_e32 v145, v147
	v_pk_add_f32 v[144:145], v[148:149], v[144:145]
	s_nop 0
	v_add_f32_e32 v143, v144, v145
	v_fmamk_f32 v143, v143, 0x3b800000, v243
	v_mul_f32_e32 v144, 0x4f800000, v143
	v_cmp_gt_f32_e32 vcc, s37, v143
	v_lshlrev_b32_e32 v145, 2, v142
	v_lshl_add_u32 v145, v183, 6, v145
	v_cndmask_b32_e32 v143, v143, v144, vcc
	v_sqrt_f32_e32 v144, v143
	s_nop 0
	v_add_u32_e32 v146, -1, v144
	v_add_u32_e32 v147, 1, v144
	v_fma_f32 v148, -v146, v144, v143
	v_fma_f32 v149, -v147, v144, v143
	v_cmp_ge_f32_e64 s[42:43], 0, v148
	s_nop 1
	v_cndmask_b32_e64 v144, v144, v146, s[42:43]
	v_cmp_lt_f32_e64 s[42:43], 0, v149
	s_nop 1
	v_cndmask_b32_e64 v144, v144, v147, s[42:43]
	v_mul_f32_e32 v146, 0x37800000, v144
	v_cndmask_b32_e32 v144, v144, v146, vcc
	v_cmp_class_f32_e32 vcc, v143, v241
	v_cmp_eq_u32_e64 s[42:43], 0, v183
	s_nop 0
	v_cndmask_b32_e32 v144, v144, v143, vcc
	v_div_scale_f32 v146, s[6:7], v144, v144, 1.0
	v_rcp_f32_e32 v147, v146
	v_div_scale_f32 v148, vcc, 1.0, v144, 1.0
	v_xor_b32_e32 v143, 64, v145
	v_fma_f32 v149, -v146, v147, 1.0
	v_fmac_f32_e32 v147, v149, v147
	v_mul_f32_e32 v149, v148, v147
	v_fma_f32 v150, -v146, v149, v148
	v_fmac_f32_e32 v149, v150, v147
	v_fma_f32 v146, -v146, v149, v148
	v_div_fmas_f32 v146, v146, v147, v149
	v_div_fixup_f32 v170, v146, v144, 1.0
	v_pk_mul_f32 v[162:163], v[128:129], v[170:171] op_sel_hi:[1,0]
	v_pk_mul_f32 v[164:165], v[126:127], v[170:171] op_sel_hi:[1,0]
	v_pk_mul_f32 v[166:167], v[124:125], v[170:171] op_sel_hi:[1,0]
	v_pk_mul_f32 v[168:169], v[122:123], v[170:171] op_sel_hi:[1,0]
	v_mul_f32_e32 v122, v165, v165
	v_mul_f32_e32 v123, v163, v163
	v_mul_f32_e32 v124, v169, v169
	v_mul_f32_e32 v125, v167, v167
	v_fmac_f32_e32 v122, v164, v164
	v_fmac_f32_e32 v123, v162, v162
	v_fmac_f32_e32 v124, v168, v168
	v_fmac_f32_e32 v125, v166, v166
	v_add_f32_e32 v122, v122, v123
	v_add_f32_e32 v123, v124, v125
	v_add_f32_e32 v122, v122, v123
	ds_bpermute_b32 v123, v143, v122
	v_xor_b32_e32 v171, 0x80, v145
	s_waitcnt lgkmcnt(0)
	v_add_f32_e32 v122, v122, v123
	ds_bpermute_b32 v123, v171, v122
	s_and_saveexec_b64 s[10:11], s[42:43]
	s_cbranch_execz .LBB0_304
	v_lshl_add_u32 v124, v160, 4, s71
	s_waitcnt lgkmcnt(0)
	v_add_f32_e32 v122, v122, v123
	ds_write_b32 v124, v122
.LBB0_304:
	s_or_b64 exec, exec, s[10:11]
	v_add_u32_e32 v150, 16, v160
	v_ashrrev_i32_e32 v151, 31, v150
	s_waitcnt lgkmcnt(0)
	v_lshl_add_u64 v[122:123], v[150:151], 4, s[0:1]
	s_waitcnt vmcnt(6)
	v_mov_b64_e32 v[122:123], v[188:189]
	v_mov_b64_e32 v[124:125], v[190:191]
	v_mov_b32_e32 v126, v123
	v_mov_b32_e32 v127, v124
	v_mov_b32_e32 v123, v125
	v_pk_add_f32 v[122:123], v[126:127], v[122:123]
	s_nop 0
	v_add_f32_e32 v122, v122, v123
	v_fmamk_f32 v122, v122, 0x3b800000, v243
	v_rsq_f32_e32 v172, v122
	s_nop 0
	v_pk_mul_f32 v[152:153], v[120:121], v[172:173] op_sel_hi:[1,0]
	v_pk_mul_f32 v[154:155], v[118:119], v[172:173] op_sel_hi:[1,0]
	v_pk_mul_f32 v[156:157], v[116:117], v[172:173] op_sel_hi:[1,0]
	v_pk_mul_f32 v[158:159], v[114:115], v[172:173] op_sel_hi:[1,0]
	v_mul_f32_e32 v114, v155, v155
	v_mul_f32_e32 v115, v153, v153
	v_mul_f32_e32 v116, v159, v159
	v_mul_f32_e32 v117, v157, v157
	v_fmac_f32_e32 v114, v154, v154
	v_fmac_f32_e32 v115, v152, v152
	v_fmac_f32_e32 v116, v158, v158
	v_fmac_f32_e32 v117, v156, v156
	v_add_f32_e32 v114, v114, v115
	v_add_f32_e32 v115, v116, v117
	v_add_f32_e32 v114, v114, v115
	ds_bpermute_b32 v115, v143, v114
	s_waitcnt lgkmcnt(0)
	v_add_f32_e32 v114, v114, v115
	ds_bpermute_b32 v115, v171, v114
	s_and_saveexec_b64 s[10:11], s[42:43]
	s_cbranch_execz .LBB0_306
	v_lshl_add_u32 v116, v150, 4, s71
	s_waitcnt lgkmcnt(0)
	v_add_f32_e32 v114, v114, v115
	ds_write_b32 v116, v114
.LBB0_306:
	s_or_b64 exec, exec, s[10:11]
	v_add_u32_e32 v126, 32, v160
	v_ashrrev_i32_e32 v127, 31, v126
	s_waitcnt lgkmcnt(0)
	v_lshl_add_u64 v[114:115], v[126:127], 4, s[0:1]
	s_waitcnt vmcnt(5)
	v_mov_b64_e32 v[114:115], v[192:193]
	v_mov_b64_e32 v[116:117], v[194:195]
	v_mov_b32_e32 v118, v115
	v_mov_b32_e32 v119, v116
	v_mov_b32_e32 v115, v117
	v_pk_add_f32 v[114:115], v[118:119], v[114:115]
	s_nop 0
	v_add_f32_e32 v114, v114, v115
	v_fmamk_f32 v114, v114, 0x3b800000, v243
	v_rsq_f32_e32 v114, v114
	s_nop 0
	v_pk_mul_f32 v[128:129], v[112:113], v[114:115] op_sel_hi:[1,0]
	v_pk_mul_f32 v[144:145], v[110:111], v[114:115] op_sel_hi:[1,0]
	v_pk_mul_f32 v[146:147], v[108:109], v[114:115] op_sel_hi:[1,0]
	v_pk_mul_f32 v[148:149], v[106:107], v[114:115] op_sel_hi:[1,0]
	v_mul_f32_e32 v106, v145, v145
	v_mul_f32_e32 v107, v129, v129
	v_mul_f32_e32 v108, v149, v149
	v_mul_f32_e32 v109, v147, v147
	v_fmac_f32_e32 v106, v144, v144
	v_fmac_f32_e32 v107, v128, v128
	v_fmac_f32_e32 v108, v148, v148
	v_fmac_f32_e32 v109, v146, v146
	v_add_f32_e32 v106, v106, v107
	v_add_f32_e32 v107, v108, v109
	v_add_f32_e32 v106, v106, v107
	ds_bpermute_b32 v107, v143, v106
	s_waitcnt lgkmcnt(0)
	v_add_f32_e32 v106, v106, v107
	ds_bpermute_b32 v107, v171, v106
	s_and_saveexec_b64 s[10:11], s[42:43]
	s_cbranch_execz .LBB0_308
	v_lshl_add_u32 v108, v126, 4, s71
	s_waitcnt lgkmcnt(0)
	v_add_f32_e32 v106, v106, v107
	ds_write_b32 v108, v106
.LBB0_308:
	s_or_b64 exec, exec, s[10:11]
	v_add_u32_e32 v116, 48, v160
	v_ashrrev_i32_e32 v117, 31, v116
	s_waitcnt lgkmcnt(0)
	v_lshl_add_u64 v[106:107], v[116:117], 4, s[0:1]
	s_waitcnt vmcnt(4)
	v_mov_b64_e32 v[106:107], v[196:197]
	v_mov_b64_e32 v[108:109], v[198:199]
	v_mov_b32_e32 v110, v107
	v_mov_b32_e32 v111, v108
	v_mov_b32_e32 v107, v109
	v_pk_add_f32 v[106:107], v[110:111], v[106:107]
	s_nop 0
	v_add_f32_e32 v106, v106, v107
	v_fmamk_f32 v106, v106, 0x3b800000, v243
	v_rsq_f32_e32 v112, v106
	s_nop 0
	v_pk_mul_f32 v[118:119], v[104:105], v[112:113] op_sel_hi:[1,0]
	v_pk_mul_f32 v[120:121], v[102:103], v[112:113] op_sel_hi:[1,0]
	v_pk_mul_f32 v[122:123], v[100:101], v[112:113] op_sel_hi:[1,0]
	v_pk_mul_f32 v[124:125], v[98:99], v[112:113] op_sel_hi:[1,0]
	v_mul_f32_e32 v98, v121, v121
	v_mul_f32_e32 v99, v119, v119
	v_mul_f32_e32 v100, v125, v125
	v_mul_f32_e32 v101, v123, v123
	v_fmac_f32_e32 v98, v120, v120
	v_fmac_f32_e32 v99, v118, v118
	v_fmac_f32_e32 v100, v124, v124
	v_fmac_f32_e32 v101, v122, v122
	v_add_f32_e32 v98, v98, v99
	v_add_f32_e32 v99, v100, v101
	v_add_f32_e32 v98, v98, v99
	ds_bpermute_b32 v99, v143, v98
	s_waitcnt lgkmcnt(0)
	v_add_f32_e32 v98, v98, v99
	ds_bpermute_b32 v99, v171, v98
	s_and_saveexec_b64 s[10:11], s[42:43]
	s_cbranch_execz .LBB0_310
	v_lshl_add_u32 v100, v116, 4, s71
	s_waitcnt lgkmcnt(0)
	v_add_f32_e32 v98, v98, v99
	ds_write_b32 v100, v98
.LBB0_310:
	s_or_b64 exec, exec, s[10:11]
	v_add_u32_e32 v98, 0x80, v160
	s_waitcnt lgkmcnt(0)
	v_ashrrev_i32_e32 v99, 31, v98
	v_lshl_add_u64 v[100:101], v[98:99], 4, s[0:1]
	s_waitcnt vmcnt(3)
	v_mov_b64_e32 v[100:101], v[200:201]
	v_mov_b64_e32 v[102:103], v[202:203]
	v_mov_b32_e32 v104, v101
	v_mov_b32_e32 v105, v102
	v_mov_b32_e32 v101, v103
	v_pk_add_f32 v[100:101], v[104:105], v[100:101]
	s_nop 0
	v_add_f32_e32 v100, v100, v101
	v_fmamk_f32 v100, v100, 0x3b800000, v243
	v_rsq_f32_e32 v174, v100
	s_nop 0
	v_pk_mul_f32 v[104:105], v[96:97], v[174:175] op_sel_hi:[1,0]
	v_pk_mul_f32 v[106:107], v[94:95], v[174:175] op_sel_hi:[1,0]
	v_pk_mul_f32 v[108:109], v[92:93], v[174:175] op_sel_hi:[1,0]
	v_pk_mul_f32 v[110:111], v[90:91], v[174:175] op_sel_hi:[1,0]
	v_mul_f32_e32 v90, v107, v107
	v_mul_f32_e32 v91, v105, v105
	v_mul_f32_e32 v92, v111, v111
	v_mul_f32_e32 v93, v109, v109
	v_fmac_f32_e32 v90, v106, v106
	v_fmac_f32_e32 v91, v104, v104
	v_fmac_f32_e32 v92, v110, v110
	v_fmac_f32_e32 v93, v108, v108
	v_add_f32_e32 v90, v90, v91
	v_add_f32_e32 v91, v92, v93
	v_add_f32_e32 v90, v90, v91
	ds_bpermute_b32 v91, v143, v90
	s_waitcnt lgkmcnt(0)
	v_add_f32_e32 v90, v90, v91
	ds_bpermute_b32 v91, v171, v90
	s_and_saveexec_b64 s[10:11], s[42:43]
	s_cbranch_execz .LBB0_312
	v_lshl_add_u32 v92, v98, 4, s71
	s_waitcnt lgkmcnt(0)
	v_add_f32_e32 v90, v90, v91
	ds_write_b32 v92, v90
.LBB0_312:
	s_or_b64 exec, exec, s[10:11]
	v_add_u32_e32 v90, 0x90, v160
	s_waitcnt lgkmcnt(0)
	v_ashrrev_i32_e32 v91, 31, v90
	v_lshl_add_u64 v[92:93], v[90:91], 4, s[0:1]
	s_waitcnt vmcnt(2)
	v_mov_b64_e32 v[92:93], v[204:205]
	v_mov_b64_e32 v[94:95], v[206:207]
	v_mov_b32_e32 v96, v93
	v_mov_b32_e32 v97, v94
	v_mov_b32_e32 v93, v95
	v_pk_add_f32 v[92:93], v[96:97], v[92:93]
	s_nop 0
	v_add_f32_e32 v92, v92, v93
	v_fmamk_f32 v92, v92, 0x3b800000, v243
	v_rsq_f32_e32 v176, v92
	s_nop 0
	v_pk_mul_f32 v[94:95], v[88:89], v[176:177] op_sel_hi:[1,0]
	v_pk_mul_f32 v[96:97], v[86:87], v[176:177] op_sel_hi:[1,0]
	v_pk_mul_f32 v[100:101], v[84:85], v[176:177] op_sel_hi:[1,0]
	v_pk_mul_f32 v[102:103], v[82:83], v[176:177] op_sel_hi:[1,0]
	v_mul_f32_e32 v82, v97, v97
	v_mul_f32_e32 v83, v95, v95
	v_mul_f32_e32 v84, v103, v103
	v_mul_f32_e32 v85, v101, v101
	v_fmac_f32_e32 v82, v96, v96
	v_fmac_f32_e32 v83, v94, v94
	v_fmac_f32_e32 v84, v102, v102
	v_fmac_f32_e32 v85, v100, v100
	v_add_f32_e32 v82, v82, v83
	v_add_f32_e32 v83, v84, v85
	v_add_f32_e32 v82, v82, v83
	ds_bpermute_b32 v83, v143, v82
	s_waitcnt lgkmcnt(0)
	v_add_f32_e32 v82, v82, v83
	ds_bpermute_b32 v83, v171, v82
	s_and_saveexec_b64 s[10:11], s[42:43]
	s_cbranch_execz .LBB0_314
	v_lshl_add_u32 v84, v90, 4, s71
	s_waitcnt lgkmcnt(0)
	v_add_f32_e32 v82, v82, v83
	ds_write_b32 v84, v82
.LBB0_314:
	s_or_b64 exec, exec, s[10:11]
	v_add_u32_e32 v82, 0xa0, v160
	s_waitcnt lgkmcnt(0)
	v_ashrrev_i32_e32 v83, 31, v82
	v_lshl_add_u64 v[84:85], v[82:83], 4, s[0:1]
	s_waitcnt vmcnt(1)
	v_mov_b64_e32 v[84:85], v[208:209]
	v_mov_b64_e32 v[86:87], v[210:211]
	v_mov_b32_e32 v88, v85
	v_mov_b32_e32 v89, v86
	v_mov_b32_e32 v85, v87
	v_pk_add_f32 v[84:85], v[88:89], v[84:85]
	s_nop 0
	v_add_f32_e32 v84, v84, v85
	v_fmamk_f32 v84, v84, 0x3b800000, v243
	v_rsq_f32_e32 v178, v84
	s_nop 0
	v_pk_mul_f32 v[84:85], v[80:81], v[178:179] op_sel_hi:[1,0]
	v_pk_mul_f32 v[86:87], v[78:79], v[178:179] op_sel_hi:[1,0]
	v_pk_mul_f32 v[88:89], v[76:77], v[178:179] op_sel_hi:[1,0]
	v_pk_mul_f32 v[92:93], v[74:75], v[178:179] op_sel_hi:[1,0]
	v_mul_f32_e32 v74, v87, v87
	v_mul_f32_e32 v75, v85, v85
	v_mul_f32_e32 v76, v93, v93
	v_mul_f32_e32 v77, v89, v89
	v_fmac_f32_e32 v74, v86, v86
	v_fmac_f32_e32 v75, v84, v84
	v_fmac_f32_e32 v76, v92, v92
	v_fmac_f32_e32 v77, v88, v88
	v_add_f32_e32 v74, v74, v75
	v_add_f32_e32 v75, v76, v77
	v_add_f32_e32 v74, v74, v75
	ds_bpermute_b32 v75, v143, v74
	s_waitcnt lgkmcnt(0)
	v_add_f32_e32 v74, v74, v75
	ds_bpermute_b32 v75, v171, v74
	s_and_saveexec_b64 s[10:11], s[42:43]
	s_cbranch_execz .LBB0_316
	v_lshl_add_u32 v76, v82, 4, s71
	s_waitcnt lgkmcnt(0)
	v_add_f32_e32 v74, v74, v75
	ds_write_b32 v76, v74
.LBB0_316:
	s_or_b64 exec, exec, s[10:11]
	v_add_u32_e32 v74, 0xb0, v160
	s_waitcnt lgkmcnt(0)
	v_ashrrev_i32_e32 v75, 31, v74
	v_lshl_add_u64 v[76:77], v[74:75], 4, s[0:1]
	s_waitcnt vmcnt(0)
	v_mov_b64_e32 v[76:77], v[212:213]
	v_mov_b64_e32 v[78:79], v[214:215]
	v_mov_b32_e32 v80, v77
	v_mov_b32_e32 v81, v78
	v_mov_b32_e32 v77, v79
	v_pk_add_f32 v[76:77], v[80:81], v[76:77]
	s_nop 0
	v_add_f32_e32 v76, v76, v77
	v_fmamk_f32 v76, v76, 0x3b800000, v243
	v_rsq_f32_e32 v80, v76
	s_nop 0
	v_pk_mul_f32 v[72:73], v[72:73], v[80:81] op_sel_hi:[1,0]
	v_pk_mul_f32 v[70:71], v[70:71], v[80:81] op_sel_hi:[1,0]
	v_pk_mul_f32 v[76:77], v[68:69], v[80:81] op_sel_hi:[1,0]
	v_pk_mul_f32 v[78:79], v[66:67], v[80:81] op_sel_hi:[1,0]
	v_mul_f32_e32 v66, v71, v71
	v_mul_f32_e32 v67, v73, v73
	v_mul_f32_e32 v68, v79, v79
	v_mul_f32_e32 v69, v77, v77
	v_fmac_f32_e32 v66, v70, v70
	v_fmac_f32_e32 v67, v72, v72
	v_fmac_f32_e32 v68, v78, v78
	v_fmac_f32_e32 v69, v76, v76
	v_add_f32_e32 v66, v66, v67
	v_add_f32_e32 v67, v68, v69
	v_add_f32_e32 v66, v66, v67
	ds_bpermute_b32 v67, v143, v66
	v_lshlrev_b32_e32 v143, 4, v74
	s_waitcnt lgkmcnt(0)
	v_add_f32_e32 v66, v66, v67
	ds_bpermute_b32 v67, v171, v66
	s_and_saveexec_b64 s[0:1], s[42:43]
	s_cbranch_execz .LBB0_318
	v_add_u32_e32 v68, s71, v143
	s_waitcnt lgkmcnt(0)
	v_add_f32_e32 v66, v66, v67
	ds_write_b32 v68, v66

.LBB0_526:
	s_waitcnt vmcnt(0)
	v_mov_b32_e32 v154, v1
	v_mov_b32_e32 v146, v171
	s_ashr_i32 s1, s0, 31
	s_lshl_b64 s[0:1], s[0:1], 8
	v_lshlrev_b32_e32 v142, 2, v146
	v_readlane_b32 s8, v251, 0
	s_add_u32 s0, s0, s74
	v_ashrrev_i32_e32 v143, 31, v142
	v_readlane_b32 s10, v251, 2
	v_readlane_b32 s11, v251, 3
	s_addc_u32 s1, s1, s79
	v_ashrrev_i32_e32 v155, 31, v154
	v_lshl_add_u64 v[144:145], v[142:143], 2, s[10:11]
	v_lshlrev_b32_e32 v142, 2, v154
	v_lshl_add_u64 v[168:169], s[0:1], 0, v[154:155]
	v_lshl_add_u32 v142, v146, 6, v142
	v_xor_b32_e32 v185, 64, v142
	v_xor_b32_e32 v184, 0x80, v142
	v_lshlrev_b64 v[142:143], 6, v[168:169]
	v_lshl_add_u64 v[142:143], v[144:145], 0, v[142:143]
	global_load_dwordx4 v[212:215], v[142:143], off
	global_load_dwordx4 v[216:219], v[142:143], off offset:1024
	global_load_dwordx4 v[220:223], v[142:143], off offset:2048
	global_load_dwordx4 v[204:207], v[142:143], off offset:3072
	v_lshl_add_u64 v[166:167], v[168:169], 0, 16
	v_lshl_add_u64 v[164:165], v[168:169], 0, 32
	v_lshl_add_u64 v[162:163], v[168:169], 0, 48
	v_lshl_add_u64 v[160:161], v[168:169], 0, s[28:29]
	s_mov_b64 s[10:11], -1
	v_and_b32_e32 v188, 3, v154
	v_and_b32_e32 v154, 8, v154
	v_readlane_b32 s9, v251, 1
	s_waitcnt vmcnt(3)
	v_mov_b64_e32 v[148:149], v[212:213]
	v_mov_b64_e32 v[150:151], v[214:215]
	v_add_f32_e32 v142, v148, v149
	v_add_f32_e32 v143, v150, v151
	v_add_f32_e32 v142, v142, v143
	ds_bpermute_b32 v143, v185, v142
	s_waitcnt lgkmcnt(0)
	v_add_f32_e32 v142, v142, v143
	ds_bpermute_b32 v143, v184, v142
	s_waitcnt lgkmcnt(0)
	v_add_f32_e32 v142, v142, v143
	v_fmamk_f32 v142, v142, 0x3a800000, v243
	s_nop 1
	s_mov_b64 s[0:1], 0x90
	v_lshl_add_u64 v[158:159], v[168:169], 0, s[0:1]
	s_mov_b64 s[0:1], 0xa0
	v_rsq_f32_e32 v170, v142
	s_nop 0
	v_lshlrev_b64 v[142:143], 6, v[166:167]
	v_lshl_add_u64 v[142:143], v[144:145], 0, v[142:143]
	v_lshl_add_u64 v[156:157], v[168:169], 0, s[0:1]
	s_mov_b64 s[0:1], 0xb0
	s_waitcnt vmcnt(2)
	v_mov_b64_e32 v[148:149], v[216:217]
	v_mov_b64_e32 v[150:151], v[218:219]
	v_add_f32_e32 v142, v148, v149
	v_add_f32_e32 v143, v150, v151
	v_add_f32_e32 v142, v142, v143
	ds_bpermute_b32 v143, v185, v142
	s_waitcnt lgkmcnt(0)
	v_add_f32_e32 v199, v142, v143
	v_lshlrev_b64 v[142:143], 6, v[164:165]
	v_lshl_add_u64 v[142:143], v[144:145], 0, v[142:143]
	ds_bpermute_b32 v200, v184, v199
	s_waitcnt vmcnt(1)
	v_mov_b64_e32 v[148:149], v[220:221]
	v_mov_b64_e32 v[150:151], v[222:223]
	v_add_f32_e32 v142, v148, v149
	v_add_f32_e32 v143, v150, v151
	v_add_f32_e32 v142, v142, v143
	ds_bpermute_b32 v143, v185, v142
	s_waitcnt lgkmcnt(0)
	v_add_f32_e32 v197, v142, v143
	v_lshlrev_b64 v[142:143], 6, v[162:163]
	v_lshl_add_u64 v[142:143], v[144:145], 0, v[142:143]
	ds_bpermute_b32 v198, v184, v197
	s_waitcnt vmcnt(0)
	v_mov_b64_e32 v[148:149], v[204:205]
	v_mov_b64_e32 v[150:151], v[206:207]
	v_add_f32_e32 v142, v148, v149
	v_add_f32_e32 v143, v150, v151
	v_add_f32_e32 v142, v142, v143
	ds_bpermute_b32 v143, v185, v142
	s_waitcnt lgkmcnt(0)
	v_add_f32_e32 v195, v142, v143
	v_lshlrev_b64 v[142:143], 6, v[160:161]
	v_lshl_add_u64 v[142:143], v[144:145], 0, v[142:143]
	global_load_dwordx4 v[212:215], v[142:143], off
	global_load_dwordx4 v[216:219], v[142:143], off offset:1024
	global_load_dwordx4 v[220:223], v[142:143], off offset:2048
	global_load_dwordx4 v[204:207], v[142:143], off offset:3072
	ds_bpermute_b32 v196, v184, v195
	s_waitcnt vmcnt(3)
	v_mov_b64_e32 v[148:149], v[212:213]
	v_mov_b64_e32 v[150:151], v[214:215]
	v_add_f32_e32 v142, v148, v149
	v_add_f32_e32 v143, v150, v151
	v_add_f32_e32 v142, v142, v143
	ds_bpermute_b32 v143, v185, v142
	s_waitcnt lgkmcnt(0)
	v_add_f32_e32 v193, v142, v143
	v_lshlrev_b64 v[142:143], 6, v[158:159]
	v_lshl_add_u64 v[142:143], v[144:145], 0, v[142:143]
	ds_bpermute_b32 v194, v184, v193
	s_waitcnt vmcnt(2)
	v_mov_b64_e32 v[148:149], v[216:217]
	v_mov_b64_e32 v[150:151], v[218:219]
	v_add_f32_e32 v142, v148, v149
	v_add_f32_e32 v143, v150, v151
	v_add_f32_e32 v142, v142, v143
	ds_bpermute_b32 v143, v185, v142
	s_waitcnt lgkmcnt(0)
	v_add_f32_e32 v191, v142, v143
	v_lshlrev_b64 v[142:143], 6, v[156:157]
	v_lshl_add_u64 v[142:143], v[144:145], 0, v[142:143]
	ds_bpermute_b32 v192, v184, v191
	s_waitcnt vmcnt(1)
	v_mov_b64_e32 v[148:149], v[220:221]
	v_mov_b64_e32 v[150:151], v[222:223]
	v_add_f32_e32 v142, v148, v149
	v_add_f32_e32 v143, v150, v151
	v_add_f32_e32 v142, v142, v143
	ds_bpermute_b32 v143, v185, v142
	s_waitcnt lgkmcnt(0)
	v_add_f32_e32 v189, v142, v143
	v_lshl_add_u64 v[142:143], v[168:169], 0, s[0:1]
	v_lshlrev_b64 v[148:149], 6, v[142:143]
	v_lshl_add_u64 v[144:145], v[144:145], 0, v[148:149]
	s_lshl_b32 s0, s4, 8
	s_or_b32 s76, s0, s78
	ds_bpermute_b32 v190, v184, v189
	s_cmp_gt_i32 s4, 7
	s_cselect_b64 s[0:1], -1, 0
	s_add_i32 s5, s76, 0xfffff800
	s_cmp_lt_i32 s4, 4
	s_cselect_b64 s[42:43], -1, 0
	s_and_b64 vcc, exec, s[0:1]
	s_waitcnt vmcnt(0)
	v_mov_b64_e32 v[148:149], v[204:205]
	v_mov_b64_e32 v[150:151], v[206:207]
	v_add_f32_e32 v144, v148, v149
	v_add_f32_e32 v145, v150, v151
	v_add_f32_e32 v144, v144, v145
	ds_bpermute_b32 v145, v185, v144
	s_waitcnt lgkmcnt(0)
	v_add_f32_e32 v186, v144, v145
	ds_bpermute_b32 v187, v184, v186
	v_lshlrev_b32_e32 v144, 3, v146
	v_add_u32_e32 v152, s5, v144
	v_or_b32_e32 v150, 4, v152
	v_add_u32_e32 v148, 32, v152
	v_add_u32_e32 v146, 36, v152
	v_ashrrev_i32_e32 v153, 31, v152
	v_ashrrev_i32_e32 v151, 31, v150
	v_ashrrev_i32_e32 v149, 31, v148
	v_ashrrev_i32_e32 v147, 31, v146
	s_cbranch_vccz .LBB0_528
	v_and_b32_e32 v145, 0xff0, v168
	v_readlane_b32 s4, v251, 51
	v_lshlrev_b32_e32 v174, 1, v145
	v_mov_b32_e32 v175, v0
	v_readlane_b32 s5, v251, 52
	v_mov_b32_e32 v155, v0
	v_ashrrev_i64 v[172:173], 2, v[168:169]
	v_lshl_add_u64 v[174:175], s[4:5], 0, v[174:175]
	v_lshl_add_u64 v[174:175], v[174:175], 0, v[154:155]
	v_lshlrev_b32_e32 v176, 1, v188
	v_mov_b32_e32 v177, v0
	v_lshlrev_b32_e32 v145, 2, v168
	v_and_b32_e32 v172, 0xfffffc00, v172
	v_lshl_add_u64 v[174:175], v[174:175], 0, v[176:177]
	v_and_b32_e32 v176, 16, v145
	v_lshl_add_u64 v[174:175], v[174:175], 0, v[176:177]
	v_lshl_add_u64 v[176:177], v[172:173], 0, v[152:153]
	v_lshlrev_b64 v[176:177], 13, v[176:177]
	v_lshl_add_u64 v[176:177], v[174:175], 0, v[176:177]
	v_pk_mul_f32 v[178:179], v[128:129], v[170:171] op_sel_hi:[1,0]
	v_pk_mul_f32 v[180:181], v[126:127], v[170:171] op_sel_hi:[1,0]
	v_cvt_pk_bf16_f32 v155, v178, v179
	v_add_co_u32_e32 v178, vcc, s19, v176
	v_cvt_pk_bf16_f32 v145, v180, v181
	s_nop 0
	v_addc_co_u32_e32 v179, vcc, 0, v177, vcc
	global_store_short_d16_hi v[178:179], v145, off
	v_add_co_u32_e32 v178, vcc, s20, v176
	global_store_short v[176:177], v145, off
	s_nop 0
	v_addc_co_u32_e32 v179, vcc, 0, v177, vcc
	v_add_co_u32_e32 v176, vcc, s21, v176
	global_store_short v[178:179], v155, off
	s_nop 0
	v_addc_co_u32_e32 v177, vcc, 0, v177, vcc
	global_store_short_d16_hi v[176:177], v155, off
	v_lshl_add_u64 v[176:177], v[172:173], 0, v[150:151]
	v_lshlrev_b64 v[176:177], 13, v[176:177]
	v_lshl_add_u64 v[176:177], v[174:175], 0, v[176:177]
	v_pk_mul_f32 v[178:179], v[124:125], v[170:171] op_sel_hi:[1,0]
	v_pk_mul_f32 v[180:181], v[122:123], v[170:171] op_sel_hi:[1,0]
	v_cvt_pk_bf16_f32 v155, v178, v179
	v_add_co_u32_e32 v178, vcc, s19, v176
	v_cvt_pk_bf16_f32 v145, v180, v181
	s_nop 0
	v_addc_co_u32_e32 v179, vcc, 0, v177, vcc
	global_store_short_d16_hi v[178:179], v145, off
	v_add_co_u32_e32 v178, vcc, s20, v176
	global_store_short v[176:177], v145, off
	s_nop 0
	v_addc_co_u32_e32 v179, vcc, 0, v177, vcc
	v_add_co_u32_e32 v176, vcc, s21, v176
	global_store_short v[178:179], v155, off
	s_nop 0
	v_addc_co_u32_e32 v177, vcc, 0, v177, vcc
	global_store_short_d16_hi v[176:177], v155, off
	v_lshl_add_u64 v[176:177], v[172:173], 0, v[148:149]
	v_lshlrev_b64 v[176:177], 13, v[176:177]
	v_lshl_add_u64 v[176:177], v[174:175], 0, v[176:177]
	v_pk_mul_f32 v[178:179], v[120:121], v[170:171] op_sel_hi:[1,0]
	v_pk_mul_f32 v[180:181], v[118:119], v[170:171] op_sel_hi:[1,0]
	v_cvt_pk_bf16_f32 v155, v178, v179
	v_add_co_u32_e32 v178, vcc, s19, v176
	v_cvt_pk_bf16_f32 v145, v180, v181
	s_nop 0
	v_addc_co_u32_e32 v179, vcc, 0, v177, vcc
	global_store_short_d16_hi v[178:179], v145, off
	v_add_co_u32_e32 v178, vcc, s20, v176
	v_lshl_add_u64 v[172:173], v[172:173], 0, v[146:147]
	s_nop 0
	v_addc_co_u32_e32 v179, vcc, 0, v177, vcc
	global_store_short v[176:177], v145, off
	v_add_co_u32_e32 v176, vcc, s21, v176
	v_lshlrev_b64 v[172:173], 13, v[172:173]
	s_nop 0
	v_addc_co_u32_e32 v177, vcc, 0, v177, vcc
	v_lshl_add_u64 v[172:173], v[174:175], 0, v[172:173]
	v_pk_mul_f32 v[174:175], v[116:117], v[170:171] op_sel_hi:[1,0]
	global_store_short v[178:179], v155, off
	global_store_short_d16_hi v[176:177], v155, off
	v_pk_mul_f32 v[176:177], v[114:115], v[170:171] op_sel_hi:[1,0]
	v_cvt_pk_bf16_f32 v155, v174, v175
	v_add_co_u32_e32 v174, vcc, 0x2000, v172
	v_cvt_pk_bf16_f32 v145, v176, v177
	s_nop 0
	v_addc_co_u32_e32 v175, vcc, 0, v173, vcc
	global_store_short_d16_hi v[174:175], v145, off
	v_add_co_u32_e32 v174, vcc, 0x4000, v172
	global_store_short v[172:173], v145, off
	s_nop 0
	v_addc_co_u32_e32 v175, vcc, 0, v173, vcc
	v_add_co_u32_e32 v172, vcc, 0x6000, v172
	global_store_short v[174:175], v155, off
	s_nop 0
	v_addc_co_u32_e32 v173, vcc, 0, v173, vcc
	global_store_short_d16_hi v[172:173], v155, off
	s_mov_b64 s[10:11], 0
